# dense waves 0-3: matrix-phase fragment address arithmetic in front of the opening barrier, three compiler no-op SALU dropped (on top of gsaddr2)
# baseline (speedup 1.0000x reference)
; #define SBAR() __builtin_amdgcn_sched_barrier(0)
; #define PK4(P, BASE, OUT) do { unsigned a0 = cvtpk(P[BASE + 0], P[BASE + 1]), a1 = cvtpk(P[BASE + 2], P[BASE + 3]);   \
;     unsigned b0 = cvtpk(P[BASE + 4], P[BASE + 5]), b1 = cvtpk(P[BASE + 6], P[BASE + 7]);                              \
;     u32x4 w = {a0, a1, b0, b1}; OUT = *reinterpret_cast<bf16x8*>(&w); } while (0)
; #define KRD(f, d0, kb) asm volatile("ds_read_b128 %0, %2 offset:%3\n\tds_read_b128 %1, %2 offset:%4" : "=&v"(f.a), "=&v"(f.b) : "v"((kb) + koff[(d0) & 3]), "i"(((d0) >> 2) * 128), "i"(((d0) >> 2) * 128 + 8192) : "memory")
; #define PP_BAR(VM) do { if (VM) { asm volatile("s_waitcnt vmcnt(4) lgkmcnt(0)\n\ts_barrier" ::: "memory"); } else { asm volatile("s_waitcnt vmcnt(0) lgkmcnt(0)\n\ts_barrier" ::: "memory"); } } while (0)
; #define PP_BAR_PLAIN() asm volatile("s_waitcnt lgkmcnt(0)\n\ts_barrier" ::: "memory")
; __device__ __forceinline__ void finishSM(f32x16& p0, f32x16& p1, float alpha, float& l_reg, bf16x8& pa0, bf16x8& pa1, bf16x8& pa2, bf16x8& pa3) {
;   for (int r = 0; r < 16; ++r) p1[r] = __builtin_amdgcn_exp2f(p1[r]);
;   float ps = 0; for (int r = 0; r < 16; ++r) ps += p0[r]; for (int r = 0; r < 16; ++r) ps += p1[r];
;   { auto rr = __builtin_amdgcn_permlane32_swap(__float_as_uint(ps), __float_as_uint(ps), false, false);
;     ps = __uint_as_float(rr[0]) + __uint_as_float(rr[1]); }
;   l_reg = l_reg * alpha + ps;
;     ...
;   PK4(p0, 0, pa0); PK4(p0, 8, pa1); PK4(p1, 0, pa2); PK4(p1, 8, pa3);
;     ...
;       if (!(MK_PREB && t + 1 < NT)) { if (!grpB) PP_BAR(t + 2 < NT); else PP_BAR_PLAIN(); }
;       else if (!grpB) PP_BAR(t + 2 < NT);
;       if (!grpB && t + 3 < NT) DMA(t + 3, (t + 3) & 3);
;       SBAR();
;       if (t + 1 < NT) {
;         const int kb_ = kbase0 + ((t + 1) & 3) * (int)SHM_K, vb_ = VBUF(t);
;         KFrag k0_, k1_; VFrag fa_, fb_;
;         KRD(k0_, 0, kb_); KRD(k1_, 1, kb_); pv_rd<0>(fa_, vb_);
.LBB0_65:
	v_exp_f32_e32 v98, v98
	v_exp_f32_e32 v99, v99
	v_exp_f32_e32 v100, v100
	v_exp_f32_e32 v101, v101
	v_exp_f32_e32 v102, v102
	v_add_f32_e32 v162, 0, v98
	v_exp_f32_e32 v103, v103
	v_add_f32_e32 v162, v99, v162
	v_exp_f32_e32 v104, v104
	v_add_f32_e32 v162, v100, v162
	v_exp_f32_e32 v105, v105
	v_add_f32_e32 v162, v101, v162
	v_exp_f32_e32 v106, v106
	v_add_f32_e32 v162, v102, v162
	v_exp_f32_e32 v107, v107
	v_add_f32_e32 v162, v103, v162
	v_exp_f32_e32 v108, v108
	v_add_f32_e32 v162, v104, v162
	v_exp_f32_e32 v109, v109
	v_add_f32_e32 v162, v105, v162
	v_exp_f32_e32 v110, v110
	v_add_f32_e32 v162, v106, v162
	v_exp_f32_e32 v111, v111
	v_add_f32_e32 v162, v107, v162
	v_exp_f32_e32 v112, v112
	v_add_f32_e32 v162, v108, v162
	v_exp_f32_e32 v113, v113
	v_add_f32_e32 v162, v109, v162
	v_exp_f32_e32 v82, v82
	v_add_f32_e32 v162, v110, v162
	v_exp_f32_e32 v83, v83
	v_add_f32_e32 v162, v111, v162
	v_exp_f32_e32 v84, v84
	v_add_f32_e32 v162, v112, v162
	v_exp_f32_e32 v85, v85
	v_add_f32_e32 v162, v113, v162
	v_exp_f32_e32 v86, v86
	v_add_f32_e32 v162, v82, v162
	v_exp_f32_e32 v87, v87
	v_add_f32_e32 v162, v83, v162
	v_exp_f32_e32 v88, v88
	v_add_f32_e32 v162, v84, v162
	v_exp_f32_e32 v89, v89
	v_add_f32_e32 v162, v85, v162
	v_exp_f32_e32 v90, v90
	v_add_f32_e32 v162, v86, v162
	v_exp_f32_e32 v91, v91
	v_add_f32_e32 v162, v87, v162
	v_exp_f32_e32 v92, v92
	v_add_f32_e32 v162, v88, v162
	v_exp_f32_e32 v93, v93
	v_add_f32_e32 v162, v89, v162
	v_exp_f32_e32 v94, v94
	v_add_f32_e32 v162, v90, v162
	v_exp_f32_e32 v95, v95
	v_add_f32_e32 v162, v91, v162
	v_exp_f32_e32 v96, v96
	v_add_f32_e32 v162, v92, v162
	v_exp_f32_e32 v97, v97
	v_add_f32_e32 v162, v93, v162
	v_add_f32_e32 v162, v94, v162
	v_add_f32_e32 v162, v95, v162
	v_add_f32_e32 v162, v96, v162
	v_add_f32_e32 v243, v97, v162
	v_mov_b32_e32 v245, v243
	v_cvt_pk_bf16_f32 v166, v82, v83
	s_nop 0
	v_permlane32_swap_b32_e32 v243, v245
	s_andn2_b64 s[42:43], exec, s[0:1]
	s_andn2_b64 vcc, exec, s[0:1]
	v_cvt_pk_bf16_f32 v174, v98, v99
	v_cvt_pk_bf16_f32 v175, v100, v101
	v_cvt_pk_bf16_f32 v176, v102, v103
	v_cvt_pk_bf16_f32 v177, v104, v105
	v_cvt_pk_bf16_f32 v170, v106, v107
	v_cvt_pk_bf16_f32 v171, v108, v109
	v_cvt_pk_bf16_f32 v172, v110, v111
	v_cvt_pk_bf16_f32 v173, v112, v113
	v_cvt_pk_bf16_f32 v167, v84, v85
	v_cvt_pk_bf16_f32 v168, v86, v87
	v_cvt_pk_bf16_f32 v169, v88, v89
	v_cvt_pk_bf16_f32 v162, v90, v91
	v_cvt_pk_bf16_f32 v163, v92, v93
	v_cvt_pk_bf16_f32 v164, v94, v95
	v_cvt_pk_bf16_f32 v165, v96, v97
	s_cbranch_vccnz .LBB0_67
	s_add_i32 vcc_hi, s86, 0xc000
	s_and_b32 vcc_hi, vcc_hi, 0xc000
	s_add_i32 vcc_lo, s13, vcc_hi
	s_add_i32 vcc_hi, s14, vcc_hi
	s_add_u32 s84, s86, 0x4000
	s_addc_u32 s85, s87, 0
	s_and_b32 s87, s84, 0xc000
	s_and_b32 s15, s86, 0xc000
	v_add_u32_e32 v248, s87, v239
	v_add_u32_e32 v247, s87, v238
	v_add_u32_e32 v246, s15, v244
	s_waitcnt vmcnt(4) lgkmcnt(0)
	s_barrier
	s_mov_b32 m0, vcc_lo
	s_nop 0
	global_load_lds_dwordx4 v210, s[16:17]
	s_mov_b32 m0, vcc_hi
	s_nop 0
	global_load_lds_dwordx4 v208, s[30:31]
	s_add_i32 m0, vcc_lo, 0x400
	s_nop 0
	global_load_lds_dwordx4 v211, s[16:17]
	s_add_i32 m0, vcc_hi, 0x400
	s_nop 0
	global_load_lds_dwordx4 v209, s[30:31]
	s_branch .Ldense_mreads
